# phase-1 bias rows moved into idle tails: rows of w_in to the 80 workgroups without a ctx split-K unit in phase 3, rows of ffn2 gate/up to the 60 workgroups without a ninth unit in phase 5
# baseline (speedup 1.0000x reference)
; __device__ __forceinline__ float bflo(unsigned u) { return __uint_as_float(u << 16); }
; __device__ __forceinline__ float bfhi(unsigned u) { return __uint_as_float(u & 0xffff0000u); }
; __device__ __forceinline__ void phase1(const Params& P) {
;     ...
;     for (int r0 = blockIdx.x * 32 + w * 4; r0 < 4352 + 5632; r0 += gridDim.x * 32) {
;         const bool first = r0 < 4352;
;         const bf16_t* wt = first ? (const bf16_t*)(P.ws + OFF_WIN) + (size_t)r0 * 1024 : (const bf16_t*)(P.ws + OFF_WGU2) + (size_t)(r0 - 4352) * 1024;
;         const float* sh = mod + (first ? 3 : 6) * 1024 + lane * 16;
;         uint4 wq[4][2];
; #pragma unroll
;         for (int i = 0; i < 4; ++i) { wq[i][0] = *(const uint4*)(wt + (size_t)i * 1024 + lane * 16); wq[i][1] = *(const uint4*)(wt + (size_t)i * 1024 + lane * 16 + 8); }
;         f32x4 s4[5][4];
; #pragma unroll
;         for (int mr = 0; mr < 5; ++mr)
; #pragma unroll
;             for (int q = 0; q < 4; ++q) s4[mr][q] = *(const f32x4*)(sh + mr * 9216 + q * 4);
;         float* BW = (float*)(P.ws + OFF_BW);
; #pragma unroll
;         for (int i = 0; i < 4; ++i) {
;             const uint4 w0 = wq[i][0], w1 = wq[i][1];
;             const float wv[16] = {bflo(w0.x), bfhi(w0.x), bflo(w0.y), bfhi(w0.y), bflo(w0.z), bfhi(w0.z), bflo(w0.w), bfhi(w0.w),
;                                   bflo(w1.x), bfhi(w1.x), bflo(w1.y), bfhi(w1.y), bflo(w1.z), bfhi(w1.z), bflo(w1.w), bfhi(w1.w)};
;             const int r = r0 + i;
; #pragma unroll
;             for (int mr = 0; mr < 5; ++mr) {
;                 float a = 0.f;
; #pragma unroll
;                 for (int q = 0; q < 4; ++q) a += s4[mr][q][0] * wv[q * 4] + s4[mr][q][1] * wv[q * 4 + 1] + s4[mr][q][2] * wv[q * 4 + 2] + s4[mr][q][3] * wv[q * 4 + 3];
;                 a = wave_sum(a);
;                 if (lane == 0) { if (first) BW[mr * 4352 + r] = a; else BW[5 * 4352 + mr * 5632 + (r - 4352)] = a; }
;             }
;         }
;     }
.Lp1n_done:
.LBB0_139:
	s_or_b64 exec, exec, s[4:5]
	s_branch .LBB0_194
	s_nop 0
	s_nop 0

; __device__ __forceinline__ float bflo(unsigned u) { return __uint_as_float(u << 16); }
; __device__ __forceinline__ float bfhi(unsigned u) { return __uint_as_float(u & 0xffff0000u); }
; __device__ __forceinline__ void phase1(const Params& P) {
;     ...
;     for (int r0 = blockIdx.x * 32 + w * 4; r0 < 4352 + 5632; r0 += gridDim.x * 32) {
;         const bool first = r0 < 4352;
;         const bf16_t* wt = first ? (const bf16_t*)(P.ws + OFF_WIN) + (size_t)r0 * 1024 : (const bf16_t*)(P.ws + OFF_WGU2) + (size_t)(r0 - 4352) * 1024;
;         const float* sh = mod + (first ? 3 : 6) * 1024 + lane * 16;
;         uint4 wq[4][2];
; #pragma unroll
;         for (int i = 0; i < 4; ++i) { wq[i][0] = *(const uint4*)(wt + (size_t)i * 1024 + lane * 16); wq[i][1] = *(const uint4*)(wt + (size_t)i * 1024 + lane * 16 + 8); }
;         f32x4 s4[5][4];
; #pragma unroll
;         for (int mr = 0; mr < 5; ++mr)
; #pragma unroll
;             for (int q = 0; q < 4; ++q) s4[mr][q] = *(const f32x4*)(sh + mr * 9216 + q * 4);
;         float* BW = (float*)(P.ws + OFF_BW);
; #pragma unroll
;         for (int i = 0; i < 4; ++i) {
;             const uint4 w0 = wq[i][0], w1 = wq[i][1];
;             const float wv[16] = {bflo(w0.x), bfhi(w0.x), bflo(w0.y), bfhi(w0.y), bflo(w0.z), bfhi(w0.z), bflo(w0.w), bfhi(w0.w),
;                                   bflo(w1.x), bfhi(w1.x), bflo(w1.y), bfhi(w1.y), bflo(w1.z), bfhi(w1.z), bflo(w1.w), bfhi(w1.w)};
;             const int r = r0 + i;
; #pragma unroll
;             for (int mr = 0; mr < 5; ++mr) {
;                 float a = 0.f;
; #pragma unroll
;                 for (int q = 0; q < 4; ++q) a += s4[mr][q][0] * wv[q * 4] + s4[mr][q][1] * wv[q * 4 + 1] + s4[mr][q][2] * wv[q * 4 + 2] + s4[mr][q][3] * wv[q * 4 + 3];
;                 a = wave_sum(a);
;                 if (lane == 0) { if (first) BW[mr * 4352 + r] = a; else BW[5 * 4352 + mr * 5632 + (r - 4352)] = a; }
;             }
;         }
;     }
.LBB0_380:
	s_barrier
	s_branch .LBB0_381
.Lbwa_entry:
	s_add_u32 s2, s68, 0x5188000
	s_addc_u32 s3, s69, 0
	v_lshlrev_b32_e32 v32, 4, v170
	s_sub_u32 s0, s33, 176
	s_lshl_b32 s0, s0, 5
	v_lshl_add_u32 v104, v171, 2, s0
	s_movk_i32 s0, 0x1100
	v_cmp_gt_i32_e32 vcc, s0, v104
	s_and_saveexec_b64 s[0:1], vcc
	s_cbranch_execz .Lbwa_end
	v_mbcnt_lo_u32_b32 v0, -1, 0
	v_mbcnt_hi_u32_b32 v0, -1, v0
	v_and_b32_e32 v1, 64, v0
	v_add_u32_e32 v1, 64, v1
	v_xor_b32_e32 v2, 1, v0
	v_cmp_lt_i32_e32 vcc, v2, v1
	v_mov_b32_e32 v107, 0
	v_lshlrev_b32_e32 v106, 6, v170
	v_cndmask_b32_e32 v2, v0, v2, vcc
	v_lshlrev_b32_e32 v114, 2, v2
	v_xor_b32_e32 v2, 2, v0
	v_cmp_lt_i32_e32 vcc, v2, v1
	s_add_u32 s10, s68, 0x1efa3000
	v_lshl_add_u64 v[108:109], s[2:3], 0, v[106:107]
	v_cndmask_b32_e32 v2, v0, v2, vcc
	v_lshlrev_b32_e32 v115, 2, v2
	v_xor_b32_e32 v2, 4, v0
	v_cmp_lt_i32_e32 vcc, v2, v1
	s_addc_u32 s11, s69, 0
	v_cmp_eq_u32_e64 s[2:3], 0, v170
	v_cndmask_b32_e32 v2, v0, v2, vcc
	v_lshlrev_b32_e32 v116, 2, v2
	v_xor_b32_e32 v2, 8, v0
	v_cmp_lt_i32_e32 vcc, v2, v1
	s_movk_i32 s30, 0xa00
	s_mov_b64 s[12:13], 0
	v_cndmask_b32_e32 v2, v0, v2, vcc
	v_lshlrev_b32_e32 v117, 2, v2
	v_xor_b32_e32 v2, 16, v0
	v_cmp_lt_i32_e32 vcc, v2, v1
	s_movk_i32 s31, 0x10ff
	s_movk_i32 s34, 0x1100
	v_cndmask_b32_e32 v2, v0, v2, vcc
	v_lshlrev_b32_e32 v118, 2, v2
	v_xor_b32_e32 v2, 32, v0
	v_cmp_lt_i32_e32 vcc, v2, v1
	v_mov_b32_e32 v120, 0x1080000
	v_mov_b32_e32 v121, 0x2100000
	v_cndmask_b32_e32 v0, v0, v2, vcc
	v_lshlrev_b32_e32 v119, 2, v0
	v_mov_b32_e32 v122, 0x6000
	v_mov_b32_e32 v123, 0x3000
	v_lshlrev_b32_e32 v110, 1, v32
	v_mov_b32_e32 v111, v107
	s_mov_b64 s[14:15], 0x1000
	s_movk_i32 s35, 0x1000
	s_mov_b64 s[16:17], 0x1800
	s_mov_b64 s[18:19], 0x9000
	s_mov_b32 s38, 0x9000
	s_mov_b64 s[20:21], 0x12000
	s_mov_b32 s39, 0x12000
	s_mov_b64 s[22:23], 0x1b000
	s_mov_b32 s40, 0x1b000
	s_mov_b64 s[24:25], 0x24000
	s_mov_b32 s41, 0x24000
	s_movk_i32 s42, 0x10ff
	v_mov_b32_e32 v124, 0x16800
	v_mov_b32_e32 v125, 0x4400
	v_mov_b32_e32 v126, 0x1c000
	v_mov_b32_e32 v127, 0x8800
	v_mov_b32_e32 v128, 0x21800
	v_mov_b32_e32 v129, 0xcc00
	v_mov_b32_e32 v130, 0x16804
	v_mov_b32_e32 v131, 0x4404
	v_mov_b32_e32 v132, 0x1c004
	v_mov_b32_e32 v133, 0x8804
	v_mov_b32_e32 v134, 0x21804
	v_mov_b32_e32 v135, 0xcc04
	v_mov_b32_e32 v136, 0x16808
	v_mov_b32_e32 v137, 0x4408
	v_mov_b32_e32 v138, 0x1c008
	v_mov_b32_e32 v139, 0x8808
	v_mov_b32_e32 v140, 0x21808
	v_mov_b32_e32 v141, 0xcc08
	v_mov_b32_e32 v142, 0x1680c
	v_mov_b32_e32 v143, 0x440c
	v_mov_b32_e32 v144, 0x1c00c
	v_mov_b32_e32 v145, 0x880c
	v_mov_b32_e32 v146, 0x2180c
	v_mov_b32_e32 v147, 0xcc0c
	s_branch .Lbwa_142

; __device__ __forceinline__ float bflo(unsigned u) { return __uint_as_float(u << 16); }
; __device__ __forceinline__ float bfhi(unsigned u) { return __uint_as_float(u & 0xffff0000u); }
; __device__ __forceinline__ void phase1(const Params& P) {
;     ...
;     for (int r0 = blockIdx.x * 32 + w * 4; r0 < 4352 + 5632; r0 += gridDim.x * 32) {
;         const bool first = r0 < 4352;
;         const bf16_t* wt = first ? (const bf16_t*)(P.ws + OFF_WIN) + (size_t)r0 * 1024 : (const bf16_t*)(P.ws + OFF_WGU2) + (size_t)(r0 - 4352) * 1024;
;         const float* sh = mod + (first ? 3 : 6) * 1024 + lane * 16;
;         uint4 wq[4][2];
; #pragma unroll
;         for (int i = 0; i < 4; ++i) { wq[i][0] = *(const uint4*)(wt + (size_t)i * 1024 + lane * 16); wq[i][1] = *(const uint4*)(wt + (size_t)i * 1024 + lane * 16 + 8); }
;         f32x4 s4[5][4];
; #pragma unroll
;         for (int mr = 0; mr < 5; ++mr)
; #pragma unroll
;             for (int q = 0; q < 4; ++q) s4[mr][q] = *(const f32x4*)(sh + mr * 9216 + q * 4);
;         float* BW = (float*)(P.ws + OFF_BW);
; #pragma unroll
;         for (int i = 0; i < 4; ++i) {
;             const uint4 w0 = wq[i][0], w1 = wq[i][1];
;             const float wv[16] = {bflo(w0.x), bfhi(w0.x), bflo(w0.y), bfhi(w0.y), bflo(w0.z), bfhi(w0.z), bflo(w0.w), bfhi(w0.w),
;                                   bflo(w1.x), bfhi(w1.x), bflo(w1.y), bfhi(w1.y), bflo(w1.z), bfhi(w1.z), bflo(w1.w), bfhi(w1.w)};
;             const int r = r0 + i;
; #pragma unroll
;             for (int mr = 0; mr < 5; ++mr) {
;                 float a = 0.f;
; #pragma unroll
;                 for (int q = 0; q < 4; ++q) a += s4[mr][q][0] * wv[q * 4] + s4[mr][q][1] * wv[q * 4 + 1] + s4[mr][q][2] * wv[q * 4 + 2] + s4[mr][q][3] * wv[q * 4 + 3];
;                 a = wave_sum(a);
;                 if (lane == 0) { if (first) BW[mr * 4352 + r] = a; else BW[5 * 4352 + mr * 5632 + (r - 4352)] = a; }
;             }
;         }
;     }
.Lbwa_end:
	s_mov_b64 exec, -1
	s_nop 0

; __device__ __forceinline__ float bflo(unsigned u) { return __uint_as_float(u << 16); }
; __device__ __forceinline__ float bfhi(unsigned u) { return __uint_as_float(u & 0xffff0000u); }
; __device__ __forceinline__ void phase1(const Params& P) {
;     ...
;     for (int r0 = blockIdx.x * 32 + w * 4; r0 < 4352 + 5632; r0 += gridDim.x * 32) {
;         const bool first = r0 < 4352;
;         const bf16_t* wt = first ? (const bf16_t*)(P.ws + OFF_WIN) + (size_t)r0 * 1024 : (const bf16_t*)(P.ws + OFF_WGU2) + (size_t)(r0 - 4352) * 1024;
;         const float* sh = mod + (first ? 3 : 6) * 1024 + lane * 16;
;         uint4 wq[4][2];
; #pragma unroll
;         for (int i = 0; i < 4; ++i) { wq[i][0] = *(const uint4*)(wt + (size_t)i * 1024 + lane * 16); wq[i][1] = *(const uint4*)(wt + (size_t)i * 1024 + lane * 16 + 8); }
;         f32x4 s4[5][4];
; #pragma unroll
;         for (int mr = 0; mr < 5; ++mr)
; #pragma unroll
;             for (int q = 0; q < 4; ++q) s4[mr][q] = *(const f32x4*)(sh + mr * 9216 + q * 4);
;         float* BW = (float*)(P.ws + OFF_BW);
; #pragma unroll
;         for (int i = 0; i < 4; ++i) {
;             const uint4 w0 = wq[i][0], w1 = wq[i][1];
;             const float wv[16] = {bflo(w0.x), bfhi(w0.x), bflo(w0.y), bfhi(w0.y), bflo(w0.z), bfhi(w0.z), bflo(w0.w), bfhi(w0.w),
;                                   bflo(w1.x), bfhi(w1.x), bflo(w1.y), bfhi(w1.y), bflo(w1.z), bfhi(w1.z), bflo(w1.w), bfhi(w1.w)};
;             const int r = r0 + i;
; #pragma unroll
;             for (int mr = 0; mr < 5; ++mr) {
;                 float a = 0.f;
; #pragma unroll
;                 for (int q = 0; q < 4; ++q) a += s4[mr][q][0] * wv[q * 4] + s4[mr][q][1] * wv[q * 4 + 1] + s4[mr][q][2] * wv[q * 4 + 2] + s4[mr][q][3] * wv[q * 4 + 3];
;                 a = wave_sum(a);
;                 if (lane == 0) { if (first) BW[mr * 4352 + r] = a; else BW[5 * 4352 + mr * 5632 + (r - 4352)] = a; }
;             }
;         }
;     }
.LBB0_962:
	s_barrier
	s_cmpk_lt_u32 s33, 0xc4
	s_cbranch_scc1 .Lbwb_skip
	s_add_u32 s2, s68, 0x5188000
	s_addc_u32 s3, s69, 0
	v_lshlrev_b32_e32 v32, 4, v170
	s_sub_u32 s0, s33, 196
	s_lshl_b32 s0, s0, 5
	s_add_u32 s0, s0, 0x1100
	v_lshl_add_u32 v104, v171, 2, s0
	s_movk_i32 s0, 0x2700
	v_cmp_gt_i32_e32 vcc, s0, v104
	s_and_saveexec_b64 s[0:1], vcc
	s_cbranch_execz .Lbwb_end
	v_mbcnt_lo_u32_b32 v0, -1, 0
	v_mbcnt_hi_u32_b32 v0, -1, v0
	v_and_b32_e32 v1, 64, v0
	v_add_u32_e32 v1, 64, v1
	v_xor_b32_e32 v2, 1, v0
	v_cmp_lt_i32_e32 vcc, v2, v1
	v_mov_b32_e32 v107, 0
	v_lshlrev_b32_e32 v106, 6, v170
	v_cndmask_b32_e32 v2, v0, v2, vcc
	v_lshlrev_b32_e32 v114, 2, v2
	v_xor_b32_e32 v2, 2, v0
	v_cmp_lt_i32_e32 vcc, v2, v1
	s_add_u32 s10, s68, 0x1efa3000
	v_lshl_add_u64 v[108:109], s[2:3], 0, v[106:107]
	v_cndmask_b32_e32 v2, v0, v2, vcc
	v_lshlrev_b32_e32 v115, 2, v2
	v_xor_b32_e32 v2, 4, v0
	v_cmp_lt_i32_e32 vcc, v2, v1
	s_addc_u32 s11, s69, 0
	v_cmp_eq_u32_e64 s[2:3], 0, v170
	v_cndmask_b32_e32 v2, v0, v2, vcc
	v_lshlrev_b32_e32 v116, 2, v2
	v_xor_b32_e32 v2, 8, v0
	v_cmp_lt_i32_e32 vcc, v2, v1
	s_movk_i32 s30, 0x780
	s_mov_b64 s[12:13], 0
	v_cndmask_b32_e32 v2, v0, v2, vcc
	v_lshlrev_b32_e32 v117, 2, v2
	v_xor_b32_e32 v2, 16, v0
	v_cmp_lt_i32_e32 vcc, v2, v1
	s_movk_i32 s31, 0x10ff
	s_movk_i32 s34, 0x1100
	v_cndmask_b32_e32 v2, v0, v2, vcc
	v_lshlrev_b32_e32 v118, 2, v2
	v_xor_b32_e32 v2, 32, v0
	v_cmp_lt_i32_e32 vcc, v2, v1
	v_mov_b32_e32 v120, 0x1080000
	v_mov_b32_e32 v121, 0x2100000
	v_cndmask_b32_e32 v0, v0, v2, vcc
	v_lshlrev_b32_e32 v119, 2, v0
	v_mov_b32_e32 v122, 0x6000
	v_mov_b32_e32 v123, 0x3000
	v_lshlrev_b32_e32 v110, 1, v32
	v_mov_b32_e32 v111, v107
	s_mov_b64 s[14:15], 0x1000
	s_movk_i32 s35, 0x1000
	s_mov_b64 s[16:17], 0x1800
	s_mov_b64 s[18:19], 0x9000
	s_mov_b32 s38, 0x9000
	s_mov_b64 s[20:21], 0x12000
	s_mov_b32 s39, 0x12000
	s_mov_b64 s[22:23], 0x1b000
	s_mov_b32 s40, 0x1b000
	s_mov_b64 s[24:25], 0x24000
	s_mov_b32 s41, 0x24000
	s_movk_i32 s42, 0x26ff
	v_mov_b32_e32 v124, 0x16800
	v_mov_b32_e32 v125, 0x4400
	v_mov_b32_e32 v126, 0x1c000
	v_mov_b32_e32 v127, 0x8800
	v_mov_b32_e32 v128, 0x21800
	v_mov_b32_e32 v129, 0xcc00
	v_mov_b32_e32 v130, 0x16804
	v_mov_b32_e32 v131, 0x4404
	v_mov_b32_e32 v132, 0x1c004
	v_mov_b32_e32 v133, 0x8804
	v_mov_b32_e32 v134, 0x21804
	v_mov_b32_e32 v135, 0xcc04
	v_mov_b32_e32 v136, 0x16808
	v_mov_b32_e32 v137, 0x4408
	v_mov_b32_e32 v138, 0x1c008
	v_mov_b32_e32 v139, 0x8808
	v_mov_b32_e32 v140, 0x21808
	v_mov_b32_e32 v141, 0xcc08
	v_mov_b32_e32 v142, 0x1680c
	v_mov_b32_e32 v143, 0x440c
	v_mov_b32_e32 v144, 0x1c00c
	v_mov_b32_e32 v145, 0x880c
	v_mov_b32_e32 v146, 0x2180c
	v_mov_b32_e32 v147, 0xcc0c
	s_branch .Lbwb_142

.Lbwb_end:
	s_mov_b64 exec, -1
	s_nop 0
	s_nop 0
	s_nop 0
	s_nop 0
	s_nop 0
	s_nop 0
	s_nop 0
	s_nop 0
	s_nop 0
	s_nop 0
	s_nop 0
	s_nop 0
	s_nop 0
	s_nop 0
.Lbwb_skip:
	s_cmp_lt_i32 s71, 7
	s_cbranch_scc1 .LBB0_1012
